# p0a G-matrix items: 8 serialized per-element load round trips become 4 dwordx4 loads and one wait (per-lane cndmask select, same roundings)
# speedup vs baseline: 1.0070x; 1.0070x over previous
.LBB7_185:
	s_or_b64 exec, exec, s[6:7]
	s_waitcnt vmcnt(0)
	v_mul_f32_e32 v26, v6, v21
	v_mul_f32_e32 v21, 0x3fb8aa3b, v26
	v_fma_f32 v27, v26, s38, -v21
	v_rndne_f32_e32 v28, v21
	v_fmac_f32_e32 v27, 0x32a5705f, v26
	v_sub_f32_e32 v21, v21, v28
	v_add_f32_e32 v21, v21, v27
	v_exp_f32_e32 v21, v21
	v_cvt_i32_f32_e32 v27, v28
	v_mul_f32_e32 v29, v22, v22
	v_fmamk_f32 v30, v29, 0x37d75334, v13
	v_cmp_ngt_f32_e32 vcc, s39, v26
	v_ldexp_f32 v21, v21, v27
	v_fmaak_f32 v30, v29, v30, 0x3d2aabf7
	v_fmamk_f32 v31, v29, 0xb94c1982, v14
	v_cndmask_b32_e32 v21, 0, v21, vcc
	v_cmp_nlt_f32_e32 vcc, s40, v26
	v_fmaak_f32 v30, v29, v30, 0xbf000004
	v_fmaak_f32 v31, v29, v31, 0xbe2aaa9d
	v_cndmask_b32_e32 v27, v11, v21, vcc
	v_lshlrev_b32_e32 v21, 30, v23
	v_and_b32_e32 v23, 1, v23
	v_fma_f32 v30, v29, v30, 1.0
	v_mul_f32_e32 v29, v29, v31
	v_fmac_f32_e32 v22, v22, v29
	v_cmp_eq_u32_e32 vcc, 0, v23
	v_lshlrev_b32_e32 v19, 6, v4
	v_sub_u32_e32 v24, v12, v19
	v_cndmask_b32_e64 v22, -v22, v30, vcc
	v_bitop3_b32 v21, v21, v22, s53 bitop3:0x6c
	v_cmp_class_f32_e64 vcc, v9, s52
	v_ashrrev_i32_e32 v24, 1, v24
	v_xor_b32_e32 v20, v20, v9
	v_cndmask_b32_e32 v29, v17, v21, vcc
	v_mul_f32_e32 v21, v25, v25
	v_fmamk_f32 v22, v21, 0xb94c1982, v14
	v_fmaak_f32 v22, v21, v22, 0xbe2aaa9d
	v_mul_f32_e32 v22, v21, v22
	v_fmac_f32_e32 v25, v25, v22
	v_fmamk_f32 v22, v21, 0x37d75334, v13
	v_fmaak_f32 v22, v21, v22, 0x3d2aabf7
	v_fmaak_f32 v22, v21, v22, 0xbf000004
	v_fma_f32 v21, v21, v22, 1.0
	v_and_b32_e32 v22, 1, v0
	v_lshlrev_b32_e32 v0, 30, v0
	v_and_b32_e32 v0, 0x80000000, v0
	v_xor_b32_e32 v0, v20, v0
	v_sub_u32_e32 v20, 31, v24
	v_cmp_eq_u32_e64 s[6:7], 0, v22
	v_cvt_f32_u32_e32 v24, v20
	v_fma_f32 v20, v27, v29, -1.0
	v_cndmask_b32_e64 v21, v21, v25, s[6:7]
	v_xor_b32_e32 v0, v0, v21
	v_cndmask_b32_e32 v0, v17, v0, vcc
	v_mul_f32_e32 v21, v27, v0
	v_mul_f32_e32 v0, v26, v24
	v_mul_f32_e32 v0, 0x3fb8aa3b, v0
	v_exp_f32_e32 v29, v0
	v_mul_f32_e32 v0, 0.15915494, v9
	v_mul_f32_e32 v0, v0, v24
	v_fract_f32_e32 v0, v0
	v_cos_f32_e32 v9, v0
	v_sin_f32_e32 v30, v0
	v_mov_b32_e32 v0, v7
	v_pk_mul_f32 v[22:23], v[6:7], v[6:7]
	v_pk_mul_f32 v[24:25], v[0:1], v[20:21] op_sel:[0,1] op_sel_hi:[0,0]
	v_pk_fma_f32 v[26:27], v[6:7], v[20:21], v[24:25] op_sel_hi:[0,1,1] neg_lo:[0,0,1] neg_hi:[0,0,1]
	v_pk_add_f32 v[22:23], v[22:23], v[22:23] op_sel:[0,1] op_sel_hi:[0,1]
	v_div_scale_f32 v31, s[6:7], v23, v23, v27
	v_rcp_f32_e32 v32, v31
	v_pk_fma_f32 v[6:7], v[6:7], v[20:21], v[24:25]
	v_mul_f32_e32 v0, v29, v9
	v_mul_f32_e32 v26, v29, v30
	v_fma_f32 v7, -v31, v32, 1.0
	v_fmac_f32_e32 v32, v7, v32
	v_div_scale_f32 v7, vcc, v27, v23, v27
	v_mul_f32_e32 v9, v7, v32
	v_fma_f32 v20, -v31, v9, v7
	v_fmac_f32_e32 v9, v20, v32
	v_div_scale_f32 v20, s[6:7], v22, v22, v6
	v_rcp_f32_e32 v24, v20
	v_fma_f32 v7, -v31, v9, v7
	v_div_fmas_f32 v7, v7, v32, v9
	v_div_fixup_f32 v21, v7, v23, v27
	v_fma_f32 v7, -v20, v24, 1.0
	v_fmac_f32_e32 v24, v7, v24
	v_div_scale_f32 v7, vcc, v6, v22, v6
	v_mul_f32_e32 v9, v7, v24
	v_fma_f32 v23, -v20, v9, v7
	v_fmac_f32_e32 v9, v23, v24
	v_fma_f32 v7, -v20, v9, v7
	v_div_fmas_f32 v7, v7, v24, v9
	v_div_fixup_f32 v20, v7, v22, v6
	v_pk_mul_f32 v[22:23], v[26:27], v[20:21] op_sel:[0,1] op_sel_hi:[0,0]
	v_and_b32_e32 v19, 0x7f, v4
	v_lshlrev_b32_e32 v4, 9, v4
	v_pk_fma_f32 v[6:7], v[0:1], v[20:21], v[22:23] neg_lo:[0,0,1] neg_hi:[0,0,1]
	v_pk_fma_f32 v[20:21], v[0:1], v[20:21], v[22:23] op_sel_hi:[0,1,1]
	v_sub_u32_e32 v4, v10, v4
	v_mov_b32_e32 v7, v21
	v_lshlrev_b64 v[20:21], 12, v[2:3]
	v_and_b32_e32 v28, 8, v4
	v_lshl_or_b32 v20, v8, 6, v20
	v_lshl_add_u64 v[2:3], s[18:19], 0, v[20:21]
	v_lshlrev_b32_e32 v0, 2, v28
	v_lshl_add_u64 v[8:9], s[26:27], 0, v[20:21]
	v_lshl_add_u64 v[2:3], v[2:3], 0, v[0:1]
	v_lshl_add_u64 v[8:9], v[8:9], 0, v[0:1]
	v_cmp_lt_u32_e32 vcc, 63, v19
	global_load_dwordx4 v[28:31], v[2:3], off
	global_load_dwordx4 v[32:35], v[2:3], off offset:16
	global_load_dwordx4 v[36:39], v[8:9], off
	global_load_dwordx4 v[40:43], v[8:9], off offset:16
	v_bfrev_b32_e32 v27, 1
	v_cndmask_b32_e32 v27, v27, v1, vcc
	s_waitcnt vmcnt(0)
	v_cndmask_b32_e32 v8, v28, v36, vcc
	v_cndmask_b32_e32 v9, v36, v28, vcc
	v_mul_f32_e32 v8, v6, v8
	v_mul_f32_e32 v9, v7, v9
	v_xor_b32_e32 v9, v27, v9
	v_add_f32_e32 v0, v8, v9
	v_cndmask_b32_e32 v8, v29, v37, vcc
	v_cndmask_b32_e32 v9, v37, v29, vcc
	v_mul_f32_e32 v8, v6, v8
	v_mul_f32_e32 v9, v7, v9
	v_xor_b32_e32 v9, v27, v9
	v_add_f32_e32 v20, v8, v9
	v_cndmask_b32_e32 v8, v30, v38, vcc
	v_cndmask_b32_e32 v9, v38, v30, vcc
	v_mul_f32_e32 v8, v6, v8
	v_mul_f32_e32 v9, v7, v9
	v_xor_b32_e32 v9, v27, v9
	v_add_f32_e32 v21, v8, v9
	v_cndmask_b32_e32 v8, v31, v39, vcc
	v_cndmask_b32_e32 v9, v39, v31, vcc
	v_mul_f32_e32 v8, v6, v8
	v_mul_f32_e32 v9, v7, v9
	v_xor_b32_e32 v9, v27, v9
	v_add_f32_e32 v22, v8, v9
	v_cndmask_b32_e32 v8, v32, v40, vcc
	v_cndmask_b32_e32 v9, v40, v32, vcc
	v_mul_f32_e32 v8, v6, v8
	v_mul_f32_e32 v9, v7, v9
	v_xor_b32_e32 v9, v27, v9
	v_add_f32_e32 v23, v8, v9
	v_cndmask_b32_e32 v8, v33, v41, vcc
	v_cndmask_b32_e32 v9, v41, v33, vcc
	v_mul_f32_e32 v8, v6, v8
	v_mul_f32_e32 v9, v7, v9
	v_xor_b32_e32 v9, v27, v9
	v_add_f32_e32 v24, v8, v9
	v_cndmask_b32_e32 v8, v34, v42, vcc
	v_cndmask_b32_e32 v9, v42, v34, vcc
	v_mul_f32_e32 v8, v6, v8
	v_mul_f32_e32 v9, v7, v9
	v_xor_b32_e32 v9, v27, v9
	v_add_f32_e32 v25, v8, v9
	v_cndmask_b32_e32 v8, v35, v43, vcc
	v_cndmask_b32_e32 v9, v43, v35, vcc
	v_mul_f32_e32 v8, v6, v8
	v_mul_f32_e32 v9, v7, v9
	v_xor_b32_e32 v9, v27, v9
	v_add_f32_e32 v26, v8, v9
	s_mov_b64 s[6:7], exec
	s_branch .LBB7_176
